# phase-0 adaLN modulation item rewritten by hand: all 64 w_ada and 36 c loads issued up front (was 36+16 serialized load->wait round trips), f32 fma accumulation order unchanged
# speedup vs baseline: 1.0476x; 1.0137x over previous
.LBB0_84:
	s_andn2_saveexec_b64 s[6:7], s[36:37]
	s_cbranch_execz .LBB0_8
	s_load_dwordx16 s[36:51], s[0:1], 0x0
	v_mov_b32_e32 v6, v193
	s_mov_b64 s[8:9], 0
	v_and_b32_e32 v2, 0xff, v6
	v_lshlrev_b32_e32 v34, 2, v2
	v_add_u32_e32 v3, v82, v34
	s_waitcnt lgkmcnt(0)
	v_lshl_add_u64 v[4:5], s[38:39], 0, v[34:35]
	v_mov_b32_e32 v7, v2
	v_and_b32_e32 v15, 15, v6
	v_add_u32_e32 v4, v88, v15
	v_ashrrev_i32_e32 v5, 31, v4
	v_lshrrev_b32_e32 v3, 4, v2
	v_lshlrev_b64 v[4:5], 2, v[4:5]
	s_mov_b32 s8, 0xc0000
	v_mad_u64_u32 v[4:5], s[8:9], v3, s8, v[4:5]
	v_lshl_add_u64 v[4:5], s[46:47], 0, v[4:5]
	global_load_dword v130, v[4:5], off
	s_mov_b64 s[10:11], 0x3000
	v_lshl_add_u64 v[18:19], v[4:5], 0, s[10:11]
	global_load_dword v131, v[18:19], off
	s_mov_b64 s[10:11], 0x6000
	v_lshl_add_u64 v[18:19], v[4:5], 0, s[10:11]
	global_load_dword v132, v[18:19], off
	s_mov_b64 s[10:11], 0x9000
	v_lshl_add_u64 v[18:19], v[4:5], 0, s[10:11]
	global_load_dword v133, v[18:19], off
	s_mov_b64 s[10:11], 0xc000
	v_lshl_add_u64 v[18:19], v[4:5], 0, s[10:11]
	global_load_dword v134, v[18:19], off
	s_mov_b64 s[10:11], 0xf000
	v_lshl_add_u64 v[18:19], v[4:5], 0, s[10:11]
	global_load_dword v135, v[18:19], off
	s_mov_b64 s[10:11], 0x12000
	v_lshl_add_u64 v[18:19], v[4:5], 0, s[10:11]
	global_load_dword v136, v[18:19], off
	s_mov_b64 s[10:11], 0x15000
	v_lshl_add_u64 v[18:19], v[4:5], 0, s[10:11]
	global_load_dword v137, v[18:19], off
	s_mov_b64 s[10:11], 0x18000
	v_lshl_add_u64 v[18:19], v[4:5], 0, s[10:11]
	global_load_dword v138, v[18:19], off
	s_mov_b64 s[10:11], 0x1b000
	v_lshl_add_u64 v[18:19], v[4:5], 0, s[10:11]
	global_load_dword v139, v[18:19], off
	s_mov_b64 s[10:11], 0x1e000
	v_lshl_add_u64 v[18:19], v[4:5], 0, s[10:11]
	global_load_dword v140, v[18:19], off
	s_mov_b64 s[10:11], 0x21000
	v_lshl_add_u64 v[18:19], v[4:5], 0, s[10:11]
	global_load_dword v141, v[18:19], off
	s_mov_b64 s[10:11], 0x24000
	v_lshl_add_u64 v[18:19], v[4:5], 0, s[10:11]
	global_load_dword v142, v[18:19], off
	s_mov_b64 s[10:11], 0x27000
	v_lshl_add_u64 v[18:19], v[4:5], 0, s[10:11]
	global_load_dword v143, v[18:19], off
	s_mov_b64 s[10:11], 0x2a000
	v_lshl_add_u64 v[18:19], v[4:5], 0, s[10:11]
	global_load_dword v144, v[18:19], off
	s_mov_b64 s[10:11], 0x2d000
	v_lshl_add_u64 v[18:19], v[4:5], 0, s[10:11]
	global_load_dword v145, v[18:19], off
	s_mov_b64 s[10:11], 0x30000
	v_lshl_add_u64 v[18:19], v[4:5], 0, s[10:11]
	global_load_dword v146, v[18:19], off
	s_mov_b64 s[10:11], 0x33000
	v_lshl_add_u64 v[18:19], v[4:5], 0, s[10:11]
	global_load_dword v147, v[18:19], off
	s_mov_b64 s[10:11], 0x36000
	v_lshl_add_u64 v[18:19], v[4:5], 0, s[10:11]
	global_load_dword v148, v[18:19], off
	s_mov_b64 s[10:11], 0x39000
	v_lshl_add_u64 v[18:19], v[4:5], 0, s[10:11]
	global_load_dword v149, v[18:19], off
	s_mov_b64 s[10:11], 0x3c000
	v_lshl_add_u64 v[18:19], v[4:5], 0, s[10:11]
	global_load_dword v150, v[18:19], off
	s_mov_b64 s[10:11], 0x3f000
	v_lshl_add_u64 v[18:19], v[4:5], 0, s[10:11]
	global_load_dword v151, v[18:19], off
	s_mov_b64 s[10:11], 0x42000
	v_lshl_add_u64 v[18:19], v[4:5], 0, s[10:11]
	global_load_dword v152, v[18:19], off
	s_mov_b64 s[10:11], 0x45000
	v_lshl_add_u64 v[18:19], v[4:5], 0, s[10:11]
	global_load_dword v153, v[18:19], off
	s_mov_b64 s[10:11], 0x48000
	v_lshl_add_u64 v[18:19], v[4:5], 0, s[10:11]
	global_load_dword v154, v[18:19], off
	s_mov_b64 s[10:11], 0x4b000
	v_lshl_add_u64 v[18:19], v[4:5], 0, s[10:11]
	global_load_dword v155, v[18:19], off
	s_mov_b64 s[10:11], 0x4e000
	v_lshl_add_u64 v[18:19], v[4:5], 0, s[10:11]
	global_load_dword v156, v[18:19], off
	s_mov_b64 s[10:11], 0x51000
	v_lshl_add_u64 v[18:19], v[4:5], 0, s[10:11]
	global_load_dword v157, v[18:19], off
	s_mov_b64 s[10:11], 0x54000
	v_lshl_add_u64 v[18:19], v[4:5], 0, s[10:11]
	global_load_dword v158, v[18:19], off
	s_mov_b64 s[10:11], 0x57000
	v_lshl_add_u64 v[18:19], v[4:5], 0, s[10:11]
	global_load_dword v159, v[18:19], off
	s_mov_b64 s[10:11], 0x5a000
	v_lshl_add_u64 v[18:19], v[4:5], 0, s[10:11]
	global_load_dword v160, v[18:19], off
	s_mov_b64 s[10:11], 0x5d000
	v_lshl_add_u64 v[18:19], v[4:5], 0, s[10:11]
	global_load_dword v161, v[18:19], off
	s_mov_b64 s[10:11], 0x60000
	v_lshl_add_u64 v[18:19], v[4:5], 0, s[10:11]
	global_load_dword v162, v[18:19], off
	s_mov_b64 s[10:11], 0x63000
	v_lshl_add_u64 v[18:19], v[4:5], 0, s[10:11]
	global_load_dword v163, v[18:19], off
	s_mov_b64 s[10:11], 0x66000
	v_lshl_add_u64 v[18:19], v[4:5], 0, s[10:11]
	global_load_dword v164, v[18:19], off
	s_mov_b64 s[10:11], 0x69000
	v_lshl_add_u64 v[18:19], v[4:5], 0, s[10:11]
	global_load_dword v165, v[18:19], off
	s_mov_b64 s[10:11], 0x6c000
	v_lshl_add_u64 v[18:19], v[4:5], 0, s[10:11]
	global_load_dword v166, v[18:19], off
	s_mov_b64 s[10:11], 0x6f000
	v_lshl_add_u64 v[18:19], v[4:5], 0, s[10:11]
	global_load_dword v167, v[18:19], off
	s_mov_b64 s[10:11], 0x72000
	v_lshl_add_u64 v[18:19], v[4:5], 0, s[10:11]
	global_load_dword v168, v[18:19], off
	s_mov_b64 s[10:11], 0x75000
	v_lshl_add_u64 v[18:19], v[4:5], 0, s[10:11]
	global_load_dword v169, v[18:19], off
	s_mov_b64 s[10:11], 0x78000
	v_lshl_add_u64 v[18:19], v[4:5], 0, s[10:11]
	global_load_dword v170, v[18:19], off
	s_mov_b64 s[10:11], 0x7b000
	v_lshl_add_u64 v[18:19], v[4:5], 0, s[10:11]
	global_load_dword v171, v[18:19], off
	s_mov_b64 s[10:11], 0x7e000
	v_lshl_add_u64 v[18:19], v[4:5], 0, s[10:11]
	global_load_dword v172, v[18:19], off
	s_mov_b64 s[10:11], 0x81000
	v_lshl_add_u64 v[18:19], v[4:5], 0, s[10:11]
	global_load_dword v173, v[18:19], off
	s_mov_b64 s[10:11], 0x84000
	v_lshl_add_u64 v[18:19], v[4:5], 0, s[10:11]
	global_load_dword v174, v[18:19], off
	s_mov_b64 s[10:11], 0x87000
	v_lshl_add_u64 v[18:19], v[4:5], 0, s[10:11]
	global_load_dword v175, v[18:19], off
	s_mov_b64 s[10:11], 0x8a000
	v_lshl_add_u64 v[18:19], v[4:5], 0, s[10:11]
	global_load_dword v176, v[18:19], off
	s_mov_b64 s[10:11], 0x8d000
	v_lshl_add_u64 v[18:19], v[4:5], 0, s[10:11]
	global_load_dword v177, v[18:19], off
	s_mov_b64 s[10:11], 0x90000
	v_lshl_add_u64 v[18:19], v[4:5], 0, s[10:11]
	global_load_dword v178, v[18:19], off
	s_mov_b64 s[10:11], 0x93000
	v_lshl_add_u64 v[18:19], v[4:5], 0, s[10:11]
	global_load_dword v179, v[18:19], off
	s_mov_b64 s[10:11], 0x96000
	v_lshl_add_u64 v[18:19], v[4:5], 0, s[10:11]
	global_load_dword v180, v[18:19], off
	s_mov_b64 s[10:11], 0x99000
	v_lshl_add_u64 v[18:19], v[4:5], 0, s[10:11]
	global_load_dword v181, v[18:19], off
	s_mov_b64 s[10:11], 0x9c000
	v_lshl_add_u64 v[18:19], v[4:5], 0, s[10:11]
	global_load_dword v182, v[18:19], off
	s_mov_b64 s[10:11], 0x9f000
	v_lshl_add_u64 v[18:19], v[4:5], 0, s[10:11]
	global_load_dword v183, v[18:19], off
	s_mov_b64 s[10:11], 0xa2000
	v_lshl_add_u64 v[18:19], v[4:5], 0, s[10:11]
	global_load_dword v184, v[18:19], off
	s_mov_b64 s[10:11], 0xa5000
	v_lshl_add_u64 v[18:19], v[4:5], 0, s[10:11]
	global_load_dword v185, v[18:19], off
	s_mov_b64 s[10:11], 0xa8000
	v_lshl_add_u64 v[18:19], v[4:5], 0, s[10:11]
	global_load_dword v186, v[18:19], off
	s_mov_b64 s[10:11], 0xab000
	v_lshl_add_u64 v[18:19], v[4:5], 0, s[10:11]
	global_load_dword v187, v[18:19], off
	s_mov_b64 s[10:11], 0xae000
	v_lshl_add_u64 v[18:19], v[4:5], 0, s[10:11]
	global_load_dword v188, v[18:19], off
	s_mov_b64 s[10:11], 0xb1000
	v_lshl_add_u64 v[18:19], v[4:5], 0, s[10:11]
	global_load_dword v189, v[18:19], off
	s_mov_b64 s[10:11], 0xb4000
	v_lshl_add_u64 v[18:19], v[4:5], 0, s[10:11]
	global_load_dword v190, v[18:19], off
	s_mov_b64 s[10:11], 0xb7000
	v_lshl_add_u64 v[18:19], v[4:5], 0, s[10:11]
	global_load_dword v191, v[18:19], off
	s_mov_b64 s[10:11], 0xba000
	v_lshl_add_u64 v[18:19], v[4:5], 0, s[10:11]
	global_load_dword v194, v[18:19], off
	s_mov_b64 s[10:11], 0xbd000
	v_lshl_add_u64 v[18:19], v[4:5], 0, s[10:11]
	global_load_dword v195, v[18:19], off
	v_lshl_add_u64 v[20:21], s[38:39], 0, v[34:35]
	v_lshl_add_u64 v[22:23], s[42:43], 0, v[34:35]
	s_mov_b64 s[10:11], 0x1000
	global_load_dword v196, v[20:21], off
	global_load_dword v197, v[20:21], off offset:1024
	global_load_dword v198, v[20:21], off offset:2048
	global_load_dword v199, v[20:21], off offset:3072
	v_lshl_add_u64 v[20:21], v[20:21], 0, s[10:11]
	global_load_dword v200, v[20:21], off
	global_load_dword v201, v[20:21], off offset:1024
	global_load_dword v202, v[20:21], off offset:2048
	global_load_dword v203, v[20:21], off offset:3072
	v_lshl_add_u64 v[20:21], v[20:21], 0, s[10:11]
	global_load_dword v204, v[20:21], off
	global_load_dword v206, v[20:21], off offset:1024
	global_load_dword v208, v[20:21], off offset:2048
	global_load_dword v209, v[20:21], off offset:3072
	v_lshl_add_u64 v[20:21], v[20:21], 0, s[10:11]
	global_load_dword v210, v[20:21], off
	global_load_dword v211, v[20:21], off offset:1024
	global_load_dword v212, v[20:21], off offset:2048
	global_load_dword v213, v[20:21], off offset:3072
	v_lshl_add_u64 v[20:21], v[20:21], 0, s[10:11]
	global_load_dword v214, v[20:21], off
	global_load_dword v215, v[20:21], off offset:1024
	global_load_dword v216, v[20:21], off offset:2048
	global_load_dword v217, v[20:21], off offset:3072
	v_lshl_add_u64 v[20:21], v[20:21], 0, s[10:11]
	global_load_dword v218, v[20:21], off
	global_load_dword v219, v[20:21], off offset:1024
	global_load_dword v220, v[20:21], off offset:2048
	global_load_dword v221, v[20:21], off offset:3072
	v_lshl_add_u64 v[20:21], v[20:21], 0, s[10:11]
	global_load_dword v222, v[20:21], off
	global_load_dword v223, v[20:21], off offset:1024
	global_load_dword v224, v[20:21], off offset:2048
	global_load_dword v225, v[20:21], off offset:3072
	v_lshl_add_u64 v[20:21], v[20:21], 0, s[10:11]
	global_load_dword v226, v[20:21], off
	global_load_dword v227, v[20:21], off offset:1024
	global_load_dword v228, v[20:21], off offset:2048
	global_load_dword v229, v[20:21], off offset:3072
	global_load_dword v230, v[22:23], off
	global_load_dword v231, v[22:23], off offset:1024
	global_load_dword v232, v[22:23], off offset:2048
	global_load_dword v233, v[22:23], off offset:3072
	v_add_u32_e32 v17, v82, v34
	s_waitcnt vmcnt(0)
	v_mul_f32_e32 v18, 0xbfb8aa3b, v196
	v_exp_f32_e32 v18, v18
	s_nop 0
	v_add_f32_e32 v18, 1.0, v18
	v_rcp_f32_e32 v18, v18
	s_nop 0
	v_mul_f32_e32 v196, v196, v18
	ds_write_b32 v17, v196
	v_mul_f32_e32 v18, 0xbfb8aa3b, v197
	v_exp_f32_e32 v18, v18
	s_nop 0
	v_add_f32_e32 v18, 1.0, v18
	v_rcp_f32_e32 v18, v18
	s_nop 0
	v_mul_f32_e32 v197, v197, v18
	ds_write_b32 v17, v197 offset:1024
	v_mul_f32_e32 v18, 0xbfb8aa3b, v198
	v_exp_f32_e32 v18, v18
	s_nop 0
	v_add_f32_e32 v18, 1.0, v18
	v_rcp_f32_e32 v18, v18
	s_nop 0
	v_mul_f32_e32 v198, v198, v18
	ds_write_b32 v17, v198 offset:2048
	v_mul_f32_e32 v18, 0xbfb8aa3b, v199
	v_exp_f32_e32 v18, v18
	s_nop 0
	v_add_f32_e32 v18, 1.0, v18
	v_rcp_f32_e32 v18, v18
	s_nop 0
	v_mul_f32_e32 v199, v199, v18
	ds_write_b32 v17, v199 offset:3072
	v_mul_f32_e32 v18, 0xbfb8aa3b, v200
	v_exp_f32_e32 v18, v18
	s_nop 0
	v_add_f32_e32 v18, 1.0, v18
	v_rcp_f32_e32 v18, v18
	s_nop 0
	v_mul_f32_e32 v200, v200, v18
	ds_write_b32 v17, v200 offset:4096
	v_mul_f32_e32 v18, 0xbfb8aa3b, v201
	v_exp_f32_e32 v18, v18
	s_nop 0
	v_add_f32_e32 v18, 1.0, v18
	v_rcp_f32_e32 v18, v18
	s_nop 0
	v_mul_f32_e32 v201, v201, v18
	ds_write_b32 v17, v201 offset:5120
	v_mul_f32_e32 v18, 0xbfb8aa3b, v202
	v_exp_f32_e32 v18, v18
	s_nop 0
	v_add_f32_e32 v18, 1.0, v18
	v_rcp_f32_e32 v18, v18
	s_nop 0
	v_mul_f32_e32 v202, v202, v18
	ds_write_b32 v17, v202 offset:6144
	v_mul_f32_e32 v18, 0xbfb8aa3b, v203
	v_exp_f32_e32 v18, v18
	s_nop 0
	v_add_f32_e32 v18, 1.0, v18
	v_rcp_f32_e32 v18, v18
	s_nop 0
	v_mul_f32_e32 v203, v203, v18
	ds_write_b32 v17, v203 offset:7168
	v_mul_f32_e32 v18, 0xbfb8aa3b, v204
	v_exp_f32_e32 v18, v18
	s_nop 0
	v_add_f32_e32 v18, 1.0, v18
	v_rcp_f32_e32 v18, v18
	s_nop 0
	v_mul_f32_e32 v204, v204, v18
	ds_write_b32 v17, v204 offset:8192
	v_mul_f32_e32 v18, 0xbfb8aa3b, v206
	v_exp_f32_e32 v18, v18
	s_nop 0
	v_add_f32_e32 v18, 1.0, v18
	v_rcp_f32_e32 v18, v18
	s_nop 0
	v_mul_f32_e32 v206, v206, v18
	ds_write_b32 v17, v206 offset:9216
	v_mul_f32_e32 v18, 0xbfb8aa3b, v208
	v_exp_f32_e32 v18, v18
	s_nop 0
	v_add_f32_e32 v18, 1.0, v18
	v_rcp_f32_e32 v18, v18
	s_nop 0
	v_mul_f32_e32 v208, v208, v18
	ds_write_b32 v17, v208 offset:10240
	v_mul_f32_e32 v18, 0xbfb8aa3b, v209
	v_exp_f32_e32 v18, v18
	s_nop 0
	v_add_f32_e32 v18, 1.0, v18
	v_rcp_f32_e32 v18, v18
	s_nop 0
	v_mul_f32_e32 v209, v209, v18
	ds_write_b32 v17, v209 offset:11264
	v_mul_f32_e32 v18, 0xbfb8aa3b, v210
	v_exp_f32_e32 v18, v18
	s_nop 0
	v_add_f32_e32 v18, 1.0, v18
	v_rcp_f32_e32 v18, v18
	s_nop 0
	v_mul_f32_e32 v210, v210, v18
	ds_write_b32 v17, v210 offset:12288
	v_mul_f32_e32 v18, 0xbfb8aa3b, v211
	v_exp_f32_e32 v18, v18
	s_nop 0
	v_add_f32_e32 v18, 1.0, v18
	v_rcp_f32_e32 v18, v18
	s_nop 0
	v_mul_f32_e32 v211, v211, v18
	ds_write_b32 v17, v211 offset:13312
	v_mul_f32_e32 v18, 0xbfb8aa3b, v212
	v_exp_f32_e32 v18, v18
	s_nop 0
	v_add_f32_e32 v18, 1.0, v18
	v_rcp_f32_e32 v18, v18
	s_nop 0
	v_mul_f32_e32 v212, v212, v18
	ds_write_b32 v17, v212 offset:14336
	v_mul_f32_e32 v18, 0xbfb8aa3b, v213
	v_exp_f32_e32 v18, v18
	s_nop 0
	v_add_f32_e32 v18, 1.0, v18
	v_rcp_f32_e32 v18, v18
	s_nop 0
	v_mul_f32_e32 v213, v213, v18
	ds_write_b32 v17, v213 offset:15360
	v_mul_f32_e32 v18, 0xbfb8aa3b, v214
	v_exp_f32_e32 v18, v18
	s_nop 0
	v_add_f32_e32 v18, 1.0, v18
	v_rcp_f32_e32 v18, v18
	s_nop 0
	v_mul_f32_e32 v214, v214, v18
	ds_write_b32 v17, v214 offset:16384
	v_mul_f32_e32 v18, 0xbfb8aa3b, v215
	v_exp_f32_e32 v18, v18
	s_nop 0
	v_add_f32_e32 v18, 1.0, v18
	v_rcp_f32_e32 v18, v18
	s_nop 0
	v_mul_f32_e32 v215, v215, v18
	ds_write_b32 v17, v215 offset:17408
	v_mul_f32_e32 v18, 0xbfb8aa3b, v216
	v_exp_f32_e32 v18, v18
	s_nop 0
	v_add_f32_e32 v18, 1.0, v18
	v_rcp_f32_e32 v18, v18
	s_nop 0
	v_mul_f32_e32 v216, v216, v18
	ds_write_b32 v17, v216 offset:18432
	v_mul_f32_e32 v18, 0xbfb8aa3b, v217
	v_exp_f32_e32 v18, v18
	s_nop 0
	v_add_f32_e32 v18, 1.0, v18
	v_rcp_f32_e32 v18, v18
	s_nop 0
	v_mul_f32_e32 v217, v217, v18
	ds_write_b32 v17, v217 offset:19456
	v_mul_f32_e32 v18, 0xbfb8aa3b, v218
	v_exp_f32_e32 v18, v18
	s_nop 0
	v_add_f32_e32 v18, 1.0, v18
	v_rcp_f32_e32 v18, v18
	s_nop 0
	v_mul_f32_e32 v218, v218, v18
	ds_write_b32 v17, v218 offset:20480
	v_mul_f32_e32 v18, 0xbfb8aa3b, v219
	v_exp_f32_e32 v18, v18
	s_nop 0
	v_add_f32_e32 v18, 1.0, v18
	v_rcp_f32_e32 v18, v18
	s_nop 0
	v_mul_f32_e32 v219, v219, v18
	ds_write_b32 v17, v219 offset:21504
	v_mul_f32_e32 v18, 0xbfb8aa3b, v220
	v_exp_f32_e32 v18, v18
	s_nop 0
	v_add_f32_e32 v18, 1.0, v18
	v_rcp_f32_e32 v18, v18
	s_nop 0
	v_mul_f32_e32 v220, v220, v18
	ds_write_b32 v17, v220 offset:22528
	v_mul_f32_e32 v18, 0xbfb8aa3b, v221
	v_exp_f32_e32 v18, v18
	s_nop 0
	v_add_f32_e32 v18, 1.0, v18
	v_rcp_f32_e32 v18, v18
	s_nop 0
	v_mul_f32_e32 v221, v221, v18
	ds_write_b32 v17, v221 offset:23552
	v_mul_f32_e32 v18, 0xbfb8aa3b, v222
	v_exp_f32_e32 v18, v18
	s_nop 0
	v_add_f32_e32 v18, 1.0, v18
	v_rcp_f32_e32 v18, v18
	s_nop 0
	v_mul_f32_e32 v222, v222, v18
	ds_write_b32 v17, v222 offset:24576
	v_mul_f32_e32 v18, 0xbfb8aa3b, v223
	v_exp_f32_e32 v18, v18
	s_nop 0
	v_add_f32_e32 v18, 1.0, v18
	v_rcp_f32_e32 v18, v18
	s_nop 0
	v_mul_f32_e32 v223, v223, v18
	ds_write_b32 v17, v223 offset:25600
	v_mul_f32_e32 v18, 0xbfb8aa3b, v224
	v_exp_f32_e32 v18, v18
	s_nop 0
	v_add_f32_e32 v18, 1.0, v18
	v_rcp_f32_e32 v18, v18
	s_nop 0
	v_mul_f32_e32 v224, v224, v18
	ds_write_b32 v17, v224 offset:26624
	v_mul_f32_e32 v18, 0xbfb8aa3b, v225
	v_exp_f32_e32 v18, v18
	s_nop 0
	v_add_f32_e32 v18, 1.0, v18
	v_rcp_f32_e32 v18, v18
	s_nop 0
	v_mul_f32_e32 v225, v225, v18
	ds_write_b32 v17, v225 offset:27648
	v_mul_f32_e32 v18, 0xbfb8aa3b, v226
	v_exp_f32_e32 v18, v18
	s_nop 0
	v_add_f32_e32 v18, 1.0, v18
	v_rcp_f32_e32 v18, v18
	s_nop 0
	v_mul_f32_e32 v226, v226, v18
	ds_write_b32 v17, v226 offset:28672
	v_mul_f32_e32 v18, 0xbfb8aa3b, v227
	v_exp_f32_e32 v18, v18
	s_nop 0
	v_add_f32_e32 v18, 1.0, v18
	v_rcp_f32_e32 v18, v18
	s_nop 0
	v_mul_f32_e32 v227, v227, v18
	ds_write_b32 v17, v227 offset:29696
	v_mul_f32_e32 v18, 0xbfb8aa3b, v228
	v_exp_f32_e32 v18, v18
	s_nop 0
	v_add_f32_e32 v18, 1.0, v18
	v_rcp_f32_e32 v18, v18
	s_nop 0
	v_mul_f32_e32 v228, v228, v18
	ds_write_b32 v17, v228 offset:30720
	v_mul_f32_e32 v18, 0xbfb8aa3b, v229
	v_exp_f32_e32 v18, v18
	s_nop 0
	v_add_f32_e32 v18, 1.0, v18
	v_rcp_f32_e32 v18, v18
	s_nop 0
	v_mul_f32_e32 v229, v229, v18
	ds_write_b32 v17, v229 offset:31744
	v_mul_f32_e32 v18, 0xbfb8aa3b, v230
	v_exp_f32_e32 v18, v18
	s_nop 0
	v_add_f32_e32 v18, 1.0, v18
	v_rcp_f32_e32 v18, v18
	s_nop 0
	v_mul_f32_e32 v230, v230, v18
	ds_write_b32 v17, v230 offset:32768
	v_mul_f32_e32 v18, 0xbfb8aa3b, v231
	v_exp_f32_e32 v18, v18
	s_nop 0
	v_add_f32_e32 v18, 1.0, v18
	v_rcp_f32_e32 v18, v18
	s_nop 0
	v_mul_f32_e32 v231, v231, v18
	ds_write_b32 v17, v231 offset:33792
	v_mul_f32_e32 v18, 0xbfb8aa3b, v232
	v_exp_f32_e32 v18, v18
	s_nop 0
	v_add_f32_e32 v18, 1.0, v18
	v_rcp_f32_e32 v18, v18
	s_nop 0
	v_mul_f32_e32 v232, v232, v18
	ds_write_b32 v17, v232 offset:34816
	v_mul_f32_e32 v18, 0xbfb8aa3b, v233
	v_exp_f32_e32 v18, v18
	s_nop 0
	v_add_f32_e32 v18, 1.0, v18
	v_rcp_f32_e32 v18, v18
	s_nop 0
	v_mul_f32_e32 v233, v233, v18
	ds_write_b32 v17, v233 offset:35840
	v_mov_b32_e32 v6, 0
	v_mov_b32_e32 v7, 0
	v_mov_b32_e32 v8, 0
	v_mov_b32_e32 v9, 0
	v_mov_b32_e32 v10, 0
	v_mov_b32_e32 v11, 0
	v_mov_b32_e32 v12, 0
	v_mov_b32_e32 v13, 0
	v_mov_b32_e32 v16, 0
	v_lshl_add_u32 v17, v3, 8, v82
	s_waitcnt lgkmcnt(0)
	s_barrier
	ds_read_b128 v[196:199], v17
	ds_read_b128 v[200:203], v17 offset:4096
	ds_read_b128 v[208:211], v17 offset:8192
	ds_read_b128 v[212:215], v17 offset:12288
	ds_read_b128 v[216:219], v17 offset:16384
	ds_read_b128 v[220:223], v17 offset:20480
	ds_read_b128 v[224:227], v17 offset:24576
	ds_read_b128 v[228:231], v17 offset:28672
	ds_read_b128 v[232:235], v17 offset:32768
	s_waitcnt lgkmcnt(0)
	v_fmac_f32_e32 v6, v130, v196
	v_fmac_f32_e32 v7, v130, v200
	v_fmac_f32_e32 v8, v130, v208
	v_fmac_f32_e32 v9, v130, v212
	v_fmac_f32_e32 v10, v130, v216
	v_fmac_f32_e32 v11, v130, v220
	v_fmac_f32_e32 v12, v130, v224
	v_fmac_f32_e32 v13, v130, v228
	v_fmac_f32_e32 v16, v130, v232
	v_fmac_f32_e32 v6, v131, v197
	v_fmac_f32_e32 v7, v131, v201
	v_fmac_f32_e32 v8, v131, v209
	v_fmac_f32_e32 v9, v131, v213
	v_fmac_f32_e32 v10, v131, v217
	v_fmac_f32_e32 v11, v131, v221
	v_fmac_f32_e32 v12, v131, v225
	v_fmac_f32_e32 v13, v131, v229
	v_fmac_f32_e32 v16, v131, v233
	v_fmac_f32_e32 v6, v132, v198
	v_fmac_f32_e32 v7, v132, v202
	v_fmac_f32_e32 v8, v132, v210
	v_fmac_f32_e32 v9, v132, v214
	v_fmac_f32_e32 v10, v132, v218
	v_fmac_f32_e32 v11, v132, v222
	v_fmac_f32_e32 v12, v132, v226
	v_fmac_f32_e32 v13, v132, v230
	v_fmac_f32_e32 v16, v132, v234
	v_fmac_f32_e32 v6, v133, v199
	v_fmac_f32_e32 v7, v133, v203
	v_fmac_f32_e32 v8, v133, v211
	v_fmac_f32_e32 v9, v133, v215
	v_fmac_f32_e32 v10, v133, v219
	v_fmac_f32_e32 v11, v133, v223
	v_fmac_f32_e32 v12, v133, v227
	v_fmac_f32_e32 v13, v133, v231
	v_fmac_f32_e32 v16, v133, v235
	ds_read_b128 v[196:199], v17 offset:16
	ds_read_b128 v[200:203], v17 offset:4112
	ds_read_b128 v[208:211], v17 offset:8208
	ds_read_b128 v[212:215], v17 offset:12304
	ds_read_b128 v[216:219], v17 offset:16400
	ds_read_b128 v[220:223], v17 offset:20496
	ds_read_b128 v[224:227], v17 offset:24592
	ds_read_b128 v[228:231], v17 offset:28688
	ds_read_b128 v[232:235], v17 offset:32784
	s_waitcnt lgkmcnt(0)
	v_fmac_f32_e32 v6, v134, v196
	v_fmac_f32_e32 v7, v134, v200
	v_fmac_f32_e32 v8, v134, v208
	v_fmac_f32_e32 v9, v134, v212
	v_fmac_f32_e32 v10, v134, v216
	v_fmac_f32_e32 v11, v134, v220
	v_fmac_f32_e32 v12, v134, v224
	v_fmac_f32_e32 v13, v134, v228
	v_fmac_f32_e32 v16, v134, v232
	v_fmac_f32_e32 v6, v135, v197
	v_fmac_f32_e32 v7, v135, v201
	v_fmac_f32_e32 v8, v135, v209
	v_fmac_f32_e32 v9, v135, v213
	v_fmac_f32_e32 v10, v135, v217
	v_fmac_f32_e32 v11, v135, v221
	v_fmac_f32_e32 v12, v135, v225
	v_fmac_f32_e32 v13, v135, v229
	v_fmac_f32_e32 v16, v135, v233
	v_fmac_f32_e32 v6, v136, v198
	v_fmac_f32_e32 v7, v136, v202
	v_fmac_f32_e32 v8, v136, v210
	v_fmac_f32_e32 v9, v136, v214
	v_fmac_f32_e32 v10, v136, v218
	v_fmac_f32_e32 v11, v136, v222
	v_fmac_f32_e32 v12, v136, v226
	v_fmac_f32_e32 v13, v136, v230
	v_fmac_f32_e32 v16, v136, v234
	v_fmac_f32_e32 v6, v137, v199
	v_fmac_f32_e32 v7, v137, v203
	v_fmac_f32_e32 v8, v137, v211
	v_fmac_f32_e32 v9, v137, v215
	v_fmac_f32_e32 v10, v137, v219
	v_fmac_f32_e32 v11, v137, v223
	v_fmac_f32_e32 v12, v137, v227
	v_fmac_f32_e32 v13, v137, v231
	v_fmac_f32_e32 v16, v137, v235
	ds_read_b128 v[196:199], v17 offset:32
	ds_read_b128 v[200:203], v17 offset:4128
	ds_read_b128 v[208:211], v17 offset:8224
	ds_read_b128 v[212:215], v17 offset:12320
	ds_read_b128 v[216:219], v17 offset:16416
	ds_read_b128 v[220:223], v17 offset:20512
	ds_read_b128 v[224:227], v17 offset:24608
	ds_read_b128 v[228:231], v17 offset:28704
	ds_read_b128 v[232:235], v17 offset:32800
	s_waitcnt lgkmcnt(0)
	v_fmac_f32_e32 v6, v138, v196
	v_fmac_f32_e32 v7, v138, v200
	v_fmac_f32_e32 v8, v138, v208
	v_fmac_f32_e32 v9, v138, v212
	v_fmac_f32_e32 v10, v138, v216
	v_fmac_f32_e32 v11, v138, v220
	v_fmac_f32_e32 v12, v138, v224
	v_fmac_f32_e32 v13, v138, v228
	v_fmac_f32_e32 v16, v138, v232
	v_fmac_f32_e32 v6, v139, v197
	v_fmac_f32_e32 v7, v139, v201
	v_fmac_f32_e32 v8, v139, v209
	v_fmac_f32_e32 v9, v139, v213
	v_fmac_f32_e32 v10, v139, v217
	v_fmac_f32_e32 v11, v139, v221
	v_fmac_f32_e32 v12, v139, v225
	v_fmac_f32_e32 v13, v139, v229
	v_fmac_f32_e32 v16, v139, v233
	v_fmac_f32_e32 v6, v140, v198
	v_fmac_f32_e32 v7, v140, v202
	v_fmac_f32_e32 v8, v140, v210
	v_fmac_f32_e32 v9, v140, v214
	v_fmac_f32_e32 v10, v140, v218
	v_fmac_f32_e32 v11, v140, v222
	v_fmac_f32_e32 v12, v140, v226
	v_fmac_f32_e32 v13, v140, v230
	v_fmac_f32_e32 v16, v140, v234
	v_fmac_f32_e32 v6, v141, v199
	v_fmac_f32_e32 v7, v141, v203
	v_fmac_f32_e32 v8, v141, v211
	v_fmac_f32_e32 v9, v141, v215
	v_fmac_f32_e32 v10, v141, v219
	v_fmac_f32_e32 v11, v141, v223
	v_fmac_f32_e32 v12, v141, v227
	v_fmac_f32_e32 v13, v141, v231
	v_fmac_f32_e32 v16, v141, v235
	ds_read_b128 v[196:199], v17 offset:48
	ds_read_b128 v[200:203], v17 offset:4144
	ds_read_b128 v[208:211], v17 offset:8240
	ds_read_b128 v[212:215], v17 offset:12336
	ds_read_b128 v[216:219], v17 offset:16432
	ds_read_b128 v[220:223], v17 offset:20528
	ds_read_b128 v[224:227], v17 offset:24624
	ds_read_b128 v[228:231], v17 offset:28720
	ds_read_b128 v[232:235], v17 offset:32816
	s_waitcnt lgkmcnt(0)
	v_fmac_f32_e32 v6, v142, v196
	v_fmac_f32_e32 v7, v142, v200
	v_fmac_f32_e32 v8, v142, v208
	v_fmac_f32_e32 v9, v142, v212
	v_fmac_f32_e32 v10, v142, v216
	v_fmac_f32_e32 v11, v142, v220
	v_fmac_f32_e32 v12, v142, v224
	v_fmac_f32_e32 v13, v142, v228
	v_fmac_f32_e32 v16, v142, v232
	v_fmac_f32_e32 v6, v143, v197
	v_fmac_f32_e32 v7, v143, v201
	v_fmac_f32_e32 v8, v143, v209
	v_fmac_f32_e32 v9, v143, v213
	v_fmac_f32_e32 v10, v143, v217
	v_fmac_f32_e32 v11, v143, v221
	v_fmac_f32_e32 v12, v143, v225
	v_fmac_f32_e32 v13, v143, v229
	v_fmac_f32_e32 v16, v143, v233
	v_fmac_f32_e32 v6, v144, v198
	v_fmac_f32_e32 v7, v144, v202
	v_fmac_f32_e32 v8, v144, v210
	v_fmac_f32_e32 v9, v144, v214
	v_fmac_f32_e32 v10, v144, v218
	v_fmac_f32_e32 v11, v144, v222
	v_fmac_f32_e32 v12, v144, v226
	v_fmac_f32_e32 v13, v144, v230
	v_fmac_f32_e32 v16, v144, v234
	v_fmac_f32_e32 v6, v145, v199
	v_fmac_f32_e32 v7, v145, v203
	v_fmac_f32_e32 v8, v145, v211
	v_fmac_f32_e32 v9, v145, v215
	v_fmac_f32_e32 v10, v145, v219
	v_fmac_f32_e32 v11, v145, v223
	v_fmac_f32_e32 v12, v145, v227
	v_fmac_f32_e32 v13, v145, v231
	v_fmac_f32_e32 v16, v145, v235
	ds_read_b128 v[196:199], v17 offset:64
	ds_read_b128 v[200:203], v17 offset:4160
	ds_read_b128 v[208:211], v17 offset:8256
	ds_read_b128 v[212:215], v17 offset:12352
	ds_read_b128 v[216:219], v17 offset:16448
	ds_read_b128 v[220:223], v17 offset:20544
	ds_read_b128 v[224:227], v17 offset:24640
	ds_read_b128 v[228:231], v17 offset:28736
	ds_read_b128 v[232:235], v17 offset:32832
	s_waitcnt lgkmcnt(0)
	v_fmac_f32_e32 v6, v146, v196
	v_fmac_f32_e32 v7, v146, v200
	v_fmac_f32_e32 v8, v146, v208
	v_fmac_f32_e32 v9, v146, v212
	v_fmac_f32_e32 v10, v146, v216
	v_fmac_f32_e32 v11, v146, v220
	v_fmac_f32_e32 v12, v146, v224
	v_fmac_f32_e32 v13, v146, v228
	v_fmac_f32_e32 v16, v146, v232
	v_fmac_f32_e32 v6, v147, v197
	v_fmac_f32_e32 v7, v147, v201
	v_fmac_f32_e32 v8, v147, v209
	v_fmac_f32_e32 v9, v147, v213
	v_fmac_f32_e32 v10, v147, v217
	v_fmac_f32_e32 v11, v147, v221
	v_fmac_f32_e32 v12, v147, v225
	v_fmac_f32_e32 v13, v147, v229
	v_fmac_f32_e32 v16, v147, v233
	v_fmac_f32_e32 v6, v148, v198
	v_fmac_f32_e32 v7, v148, v202
	v_fmac_f32_e32 v8, v148, v210
	v_fmac_f32_e32 v9, v148, v214
	v_fmac_f32_e32 v10, v148, v218
	v_fmac_f32_e32 v11, v148, v222
	v_fmac_f32_e32 v12, v148, v226
	v_fmac_f32_e32 v13, v148, v230
	v_fmac_f32_e32 v16, v148, v234
	v_fmac_f32_e32 v6, v149, v199
	v_fmac_f32_e32 v7, v149, v203
	v_fmac_f32_e32 v8, v149, v211
	v_fmac_f32_e32 v9, v149, v215
	v_fmac_f32_e32 v10, v149, v219
	v_fmac_f32_e32 v11, v149, v223
	v_fmac_f32_e32 v12, v149, v227
	v_fmac_f32_e32 v13, v149, v231
	v_fmac_f32_e32 v16, v149, v235
	ds_read_b128 v[196:199], v17 offset:80
	ds_read_b128 v[200:203], v17 offset:4176
	ds_read_b128 v[208:211], v17 offset:8272
	ds_read_b128 v[212:215], v17 offset:12368
	ds_read_b128 v[216:219], v17 offset:16464
	ds_read_b128 v[220:223], v17 offset:20560
	ds_read_b128 v[224:227], v17 offset:24656
	ds_read_b128 v[228:231], v17 offset:28752
	ds_read_b128 v[232:235], v17 offset:32848
	s_waitcnt lgkmcnt(0)
	v_fmac_f32_e32 v6, v150, v196
	v_fmac_f32_e32 v7, v150, v200
	v_fmac_f32_e32 v8, v150, v208
	v_fmac_f32_e32 v9, v150, v212
	v_fmac_f32_e32 v10, v150, v216
	v_fmac_f32_e32 v11, v150, v220
	v_fmac_f32_e32 v12, v150, v224
	v_fmac_f32_e32 v13, v150, v228
	v_fmac_f32_e32 v16, v150, v232
	v_fmac_f32_e32 v6, v151, v197
	v_fmac_f32_e32 v7, v151, v201
	v_fmac_f32_e32 v8, v151, v209
	v_fmac_f32_e32 v9, v151, v213
	v_fmac_f32_e32 v10, v151, v217
	v_fmac_f32_e32 v11, v151, v221
	v_fmac_f32_e32 v12, v151, v225
	v_fmac_f32_e32 v13, v151, v229
	v_fmac_f32_e32 v16, v151, v233
	v_fmac_f32_e32 v6, v152, v198
	v_fmac_f32_e32 v7, v152, v202
	v_fmac_f32_e32 v8, v152, v210
	v_fmac_f32_e32 v9, v152, v214
	v_fmac_f32_e32 v10, v152, v218
	v_fmac_f32_e32 v11, v152, v222
	v_fmac_f32_e32 v12, v152, v226
	v_fmac_f32_e32 v13, v152, v230
	v_fmac_f32_e32 v16, v152, v234
	v_fmac_f32_e32 v6, v153, v199
	v_fmac_f32_e32 v7, v153, v203
	v_fmac_f32_e32 v8, v153, v211
	v_fmac_f32_e32 v9, v153, v215
	v_fmac_f32_e32 v10, v153, v219
	v_fmac_f32_e32 v11, v153, v223
	v_fmac_f32_e32 v12, v153, v227
	v_fmac_f32_e32 v13, v153, v231
	v_fmac_f32_e32 v16, v153, v235
	ds_read_b128 v[196:199], v17 offset:96
	ds_read_b128 v[200:203], v17 offset:4192
	ds_read_b128 v[208:211], v17 offset:8288
	ds_read_b128 v[212:215], v17 offset:12384
	ds_read_b128 v[216:219], v17 offset:16480
	ds_read_b128 v[220:223], v17 offset:20576
	ds_read_b128 v[224:227], v17 offset:24672
	ds_read_b128 v[228:231], v17 offset:28768
	ds_read_b128 v[232:235], v17 offset:32864
	s_waitcnt lgkmcnt(0)
	v_fmac_f32_e32 v6, v154, v196
	v_fmac_f32_e32 v7, v154, v200
	v_fmac_f32_e32 v8, v154, v208
	v_fmac_f32_e32 v9, v154, v212
	v_fmac_f32_e32 v10, v154, v216
	v_fmac_f32_e32 v11, v154, v220
	v_fmac_f32_e32 v12, v154, v224
	v_fmac_f32_e32 v13, v154, v228
	v_fmac_f32_e32 v16, v154, v232
	v_fmac_f32_e32 v6, v155, v197
	v_fmac_f32_e32 v7, v155, v201
	v_fmac_f32_e32 v8, v155, v209
	v_fmac_f32_e32 v9, v155, v213
	v_fmac_f32_e32 v10, v155, v217
	v_fmac_f32_e32 v11, v155, v221
	v_fmac_f32_e32 v12, v155, v225
	v_fmac_f32_e32 v13, v155, v229
	v_fmac_f32_e32 v16, v155, v233
	v_fmac_f32_e32 v6, v156, v198
	v_fmac_f32_e32 v7, v156, v202
	v_fmac_f32_e32 v8, v156, v210
	v_fmac_f32_e32 v9, v156, v214
	v_fmac_f32_e32 v10, v156, v218
	v_fmac_f32_e32 v11, v156, v222
	v_fmac_f32_e32 v12, v156, v226
	v_fmac_f32_e32 v13, v156, v230
	v_fmac_f32_e32 v16, v156, v234
	v_fmac_f32_e32 v6, v157, v199
	v_fmac_f32_e32 v7, v157, v203
	v_fmac_f32_e32 v8, v157, v211
	v_fmac_f32_e32 v9, v157, v215
	v_fmac_f32_e32 v10, v157, v219
	v_fmac_f32_e32 v11, v157, v223
	v_fmac_f32_e32 v12, v157, v227
	v_fmac_f32_e32 v13, v157, v231
	v_fmac_f32_e32 v16, v157, v235
	ds_read_b128 v[196:199], v17 offset:112
	ds_read_b128 v[200:203], v17 offset:4208
	ds_read_b128 v[208:211], v17 offset:8304
	ds_read_b128 v[212:215], v17 offset:12400
	ds_read_b128 v[216:219], v17 offset:16496
	ds_read_b128 v[220:223], v17 offset:20592
	ds_read_b128 v[224:227], v17 offset:24688
	ds_read_b128 v[228:231], v17 offset:28784
	ds_read_b128 v[232:235], v17 offset:32880
	s_waitcnt lgkmcnt(0)
	v_fmac_f32_e32 v6, v158, v196
	v_fmac_f32_e32 v7, v158, v200
	v_fmac_f32_e32 v8, v158, v208
	v_fmac_f32_e32 v9, v158, v212
	v_fmac_f32_e32 v10, v158, v216
	v_fmac_f32_e32 v11, v158, v220
	v_fmac_f32_e32 v12, v158, v224
	v_fmac_f32_e32 v13, v158, v228
	v_fmac_f32_e32 v16, v158, v232
	v_fmac_f32_e32 v6, v159, v197
	v_fmac_f32_e32 v7, v159, v201
	v_fmac_f32_e32 v8, v159, v209
	v_fmac_f32_e32 v9, v159, v213
	v_fmac_f32_e32 v10, v159, v217
	v_fmac_f32_e32 v11, v159, v221
	v_fmac_f32_e32 v12, v159, v225
	v_fmac_f32_e32 v13, v159, v229
	v_fmac_f32_e32 v16, v159, v233
	v_fmac_f32_e32 v6, v160, v198
	v_fmac_f32_e32 v7, v160, v202
	v_fmac_f32_e32 v8, v160, v210
	v_fmac_f32_e32 v9, v160, v214
	v_fmac_f32_e32 v10, v160, v218
	v_fmac_f32_e32 v11, v160, v222
	v_fmac_f32_e32 v12, v160, v226
	v_fmac_f32_e32 v13, v160, v230
	v_fmac_f32_e32 v16, v160, v234
	v_fmac_f32_e32 v6, v161, v199
	v_fmac_f32_e32 v7, v161, v203
	v_fmac_f32_e32 v8, v161, v211
	v_fmac_f32_e32 v9, v161, v215
	v_fmac_f32_e32 v10, v161, v219
	v_fmac_f32_e32 v11, v161, v223
	v_fmac_f32_e32 v12, v161, v227
	v_fmac_f32_e32 v13, v161, v231
	v_fmac_f32_e32 v16, v161, v235
	ds_read_b128 v[196:199], v17 offset:128
	ds_read_b128 v[200:203], v17 offset:4224
	ds_read_b128 v[208:211], v17 offset:8320
	ds_read_b128 v[212:215], v17 offset:12416
	ds_read_b128 v[216:219], v17 offset:16512
	ds_read_b128 v[220:223], v17 offset:20608
	ds_read_b128 v[224:227], v17 offset:24704
	ds_read_b128 v[228:231], v17 offset:28800
	ds_read_b128 v[232:235], v17 offset:32896
	s_waitcnt lgkmcnt(0)
	v_fmac_f32_e32 v6, v162, v196
	v_fmac_f32_e32 v7, v162, v200
	v_fmac_f32_e32 v8, v162, v208
	v_fmac_f32_e32 v9, v162, v212
	v_fmac_f32_e32 v10, v162, v216
	v_fmac_f32_e32 v11, v162, v220
	v_fmac_f32_e32 v12, v162, v224
	v_fmac_f32_e32 v13, v162, v228
	v_fmac_f32_e32 v16, v162, v232
	v_fmac_f32_e32 v6, v163, v197
	v_fmac_f32_e32 v7, v163, v201
	v_fmac_f32_e32 v8, v163, v209
	v_fmac_f32_e32 v9, v163, v213
	v_fmac_f32_e32 v10, v163, v217
	v_fmac_f32_e32 v11, v163, v221
	v_fmac_f32_e32 v12, v163, v225
	v_fmac_f32_e32 v13, v163, v229
	v_fmac_f32_e32 v16, v163, v233
	v_fmac_f32_e32 v6, v164, v198
	v_fmac_f32_e32 v7, v164, v202
	v_fmac_f32_e32 v8, v164, v210
	v_fmac_f32_e32 v9, v164, v214
	v_fmac_f32_e32 v10, v164, v218
	v_fmac_f32_e32 v11, v164, v222
	v_fmac_f32_e32 v12, v164, v226
	v_fmac_f32_e32 v13, v164, v230
	v_fmac_f32_e32 v16, v164, v234
	v_fmac_f32_e32 v6, v165, v199
	v_fmac_f32_e32 v7, v165, v203
	v_fmac_f32_e32 v8, v165, v211
	v_fmac_f32_e32 v9, v165, v215
	v_fmac_f32_e32 v10, v165, v219
	v_fmac_f32_e32 v11, v165, v223
	v_fmac_f32_e32 v12, v165, v227
	v_fmac_f32_e32 v13, v165, v231
	v_fmac_f32_e32 v16, v165, v235
	ds_read_b128 v[196:199], v17 offset:144
	ds_read_b128 v[200:203], v17 offset:4240
	ds_read_b128 v[208:211], v17 offset:8336
	ds_read_b128 v[212:215], v17 offset:12432
	ds_read_b128 v[216:219], v17 offset:16528
	ds_read_b128 v[220:223], v17 offset:20624
	ds_read_b128 v[224:227], v17 offset:24720
	ds_read_b128 v[228:231], v17 offset:28816
	ds_read_b128 v[232:235], v17 offset:32912
	s_waitcnt lgkmcnt(0)
	v_fmac_f32_e32 v6, v166, v196
	v_fmac_f32_e32 v7, v166, v200
	v_fmac_f32_e32 v8, v166, v208
	v_fmac_f32_e32 v9, v166, v212
	v_fmac_f32_e32 v10, v166, v216
	v_fmac_f32_e32 v11, v166, v220
	v_fmac_f32_e32 v12, v166, v224
	v_fmac_f32_e32 v13, v166, v228
	v_fmac_f32_e32 v16, v166, v232
	v_fmac_f32_e32 v6, v167, v197
	v_fmac_f32_e32 v7, v167, v201
	v_fmac_f32_e32 v8, v167, v209
	v_fmac_f32_e32 v9, v167, v213
	v_fmac_f32_e32 v10, v167, v217
	v_fmac_f32_e32 v11, v167, v221
	v_fmac_f32_e32 v12, v167, v225
	v_fmac_f32_e32 v13, v167, v229
	v_fmac_f32_e32 v16, v167, v233
	v_fmac_f32_e32 v6, v168, v198
	v_fmac_f32_e32 v7, v168, v202
	v_fmac_f32_e32 v8, v168, v210
	v_fmac_f32_e32 v9, v168, v214
	v_fmac_f32_e32 v10, v168, v218
	v_fmac_f32_e32 v11, v168, v222
	v_fmac_f32_e32 v12, v168, v226
	v_fmac_f32_e32 v13, v168, v230
	v_fmac_f32_e32 v16, v168, v234
	v_fmac_f32_e32 v6, v169, v199
	v_fmac_f32_e32 v7, v169, v203
	v_fmac_f32_e32 v8, v169, v211
	v_fmac_f32_e32 v9, v169, v215
	v_fmac_f32_e32 v10, v169, v219
	v_fmac_f32_e32 v11, v169, v223
	v_fmac_f32_e32 v12, v169, v227
	v_fmac_f32_e32 v13, v169, v231
	v_fmac_f32_e32 v16, v169, v235
	ds_read_b128 v[196:199], v17 offset:160
	ds_read_b128 v[200:203], v17 offset:4256
	ds_read_b128 v[208:211], v17 offset:8352
	ds_read_b128 v[212:215], v17 offset:12448
	ds_read_b128 v[216:219], v17 offset:16544
	ds_read_b128 v[220:223], v17 offset:20640
	ds_read_b128 v[224:227], v17 offset:24736
	ds_read_b128 v[228:231], v17 offset:28832
	ds_read_b128 v[232:235], v17 offset:32928
	s_waitcnt lgkmcnt(0)
	v_fmac_f32_e32 v6, v170, v196
	v_fmac_f32_e32 v7, v170, v200
	v_fmac_f32_e32 v8, v170, v208
	v_fmac_f32_e32 v9, v170, v212
	v_fmac_f32_e32 v10, v170, v216
	v_fmac_f32_e32 v11, v170, v220
	v_fmac_f32_e32 v12, v170, v224
	v_fmac_f32_e32 v13, v170, v228
	v_fmac_f32_e32 v16, v170, v232
	v_fmac_f32_e32 v6, v171, v197
	v_fmac_f32_e32 v7, v171, v201
	v_fmac_f32_e32 v8, v171, v209
	v_fmac_f32_e32 v9, v171, v213
	v_fmac_f32_e32 v10, v171, v217
	v_fmac_f32_e32 v11, v171, v221
	v_fmac_f32_e32 v12, v171, v225
	v_fmac_f32_e32 v13, v171, v229
	v_fmac_f32_e32 v16, v171, v233
	v_fmac_f32_e32 v6, v172, v198
	v_fmac_f32_e32 v7, v172, v202
	v_fmac_f32_e32 v8, v172, v210
	v_fmac_f32_e32 v9, v172, v214
	v_fmac_f32_e32 v10, v172, v218
	v_fmac_f32_e32 v11, v172, v222
	v_fmac_f32_e32 v12, v172, v226
	v_fmac_f32_e32 v13, v172, v230
	v_fmac_f32_e32 v16, v172, v234
	v_fmac_f32_e32 v6, v173, v199
	v_fmac_f32_e32 v7, v173, v203
	v_fmac_f32_e32 v8, v173, v211
	v_fmac_f32_e32 v9, v173, v215
	v_fmac_f32_e32 v10, v173, v219
	v_fmac_f32_e32 v11, v173, v223
	v_fmac_f32_e32 v12, v173, v227
	v_fmac_f32_e32 v13, v173, v231
	v_fmac_f32_e32 v16, v173, v235
	ds_read_b128 v[196:199], v17 offset:176
	ds_read_b128 v[200:203], v17 offset:4272
	ds_read_b128 v[208:211], v17 offset:8368
	ds_read_b128 v[212:215], v17 offset:12464
	ds_read_b128 v[216:219], v17 offset:16560
	ds_read_b128 v[220:223], v17 offset:20656
	ds_read_b128 v[224:227], v17 offset:24752
	ds_read_b128 v[228:231], v17 offset:28848
	ds_read_b128 v[232:235], v17 offset:32944
	s_waitcnt lgkmcnt(0)
	v_fmac_f32_e32 v6, v174, v196
	v_fmac_f32_e32 v7, v174, v200
	v_fmac_f32_e32 v8, v174, v208
	v_fmac_f32_e32 v9, v174, v212
	v_fmac_f32_e32 v10, v174, v216
	v_fmac_f32_e32 v11, v174, v220
	v_fmac_f32_e32 v12, v174, v224
	v_fmac_f32_e32 v13, v174, v228
	v_fmac_f32_e32 v16, v174, v232
	v_fmac_f32_e32 v6, v175, v197
	v_fmac_f32_e32 v7, v175, v201
	v_fmac_f32_e32 v8, v175, v209
	v_fmac_f32_e32 v9, v175, v213
	v_fmac_f32_e32 v10, v175, v217
	v_fmac_f32_e32 v11, v175, v221
	v_fmac_f32_e32 v12, v175, v225
	v_fmac_f32_e32 v13, v175, v229
	v_fmac_f32_e32 v16, v175, v233
	v_fmac_f32_e32 v6, v176, v198
	v_fmac_f32_e32 v7, v176, v202
	v_fmac_f32_e32 v8, v176, v210
	v_fmac_f32_e32 v9, v176, v214
	v_fmac_f32_e32 v10, v176, v218
	v_fmac_f32_e32 v11, v176, v222
	v_fmac_f32_e32 v12, v176, v226
	v_fmac_f32_e32 v13, v176, v230
	v_fmac_f32_e32 v16, v176, v234
	v_fmac_f32_e32 v6, v177, v199
	v_fmac_f32_e32 v7, v177, v203
	v_fmac_f32_e32 v8, v177, v211
	v_fmac_f32_e32 v9, v177, v215
	v_fmac_f32_e32 v10, v177, v219
	v_fmac_f32_e32 v11, v177, v223
	v_fmac_f32_e32 v12, v177, v227
	v_fmac_f32_e32 v13, v177, v231
	v_fmac_f32_e32 v16, v177, v235
	ds_read_b128 v[196:199], v17 offset:192
	ds_read_b128 v[200:203], v17 offset:4288
	ds_read_b128 v[208:211], v17 offset:8384
	ds_read_b128 v[212:215], v17 offset:12480
	ds_read_b128 v[216:219], v17 offset:16576
	ds_read_b128 v[220:223], v17 offset:20672
	ds_read_b128 v[224:227], v17 offset:24768
	ds_read_b128 v[228:231], v17 offset:28864
	ds_read_b128 v[232:235], v17 offset:32960
	s_waitcnt lgkmcnt(0)
	v_fmac_f32_e32 v6, v178, v196
	v_fmac_f32_e32 v7, v178, v200
	v_fmac_f32_e32 v8, v178, v208
	v_fmac_f32_e32 v9, v178, v212
	v_fmac_f32_e32 v10, v178, v216
	v_fmac_f32_e32 v11, v178, v220
	v_fmac_f32_e32 v12, v178, v224
	v_fmac_f32_e32 v13, v178, v228
	v_fmac_f32_e32 v16, v178, v232
	v_fmac_f32_e32 v6, v179, v197
	v_fmac_f32_e32 v7, v179, v201
	v_fmac_f32_e32 v8, v179, v209
	v_fmac_f32_e32 v9, v179, v213
	v_fmac_f32_e32 v10, v179, v217
	v_fmac_f32_e32 v11, v179, v221
	v_fmac_f32_e32 v12, v179, v225
	v_fmac_f32_e32 v13, v179, v229
	v_fmac_f32_e32 v16, v179, v233
	v_fmac_f32_e32 v6, v180, v198
	v_fmac_f32_e32 v7, v180, v202
	v_fmac_f32_e32 v8, v180, v210
	v_fmac_f32_e32 v9, v180, v214
	v_fmac_f32_e32 v10, v180, v218
	v_fmac_f32_e32 v11, v180, v222
	v_fmac_f32_e32 v12, v180, v226
	v_fmac_f32_e32 v13, v180, v230
	v_fmac_f32_e32 v16, v180, v234
	v_fmac_f32_e32 v6, v181, v199
	v_fmac_f32_e32 v7, v181, v203
	v_fmac_f32_e32 v8, v181, v211
	v_fmac_f32_e32 v9, v181, v215
	v_fmac_f32_e32 v10, v181, v219
	v_fmac_f32_e32 v11, v181, v223
	v_fmac_f32_e32 v12, v181, v227
	v_fmac_f32_e32 v13, v181, v231
	v_fmac_f32_e32 v16, v181, v235
	ds_read_b128 v[196:199], v17 offset:208
	ds_read_b128 v[200:203], v17 offset:4304
	ds_read_b128 v[208:211], v17 offset:8400
	ds_read_b128 v[212:215], v17 offset:12496
	ds_read_b128 v[216:219], v17 offset:16592
	ds_read_b128 v[220:223], v17 offset:20688
	ds_read_b128 v[224:227], v17 offset:24784
	ds_read_b128 v[228:231], v17 offset:28880
	ds_read_b128 v[232:235], v17 offset:32976
	s_waitcnt lgkmcnt(0)
	v_fmac_f32_e32 v6, v182, v196
	v_fmac_f32_e32 v7, v182, v200
	v_fmac_f32_e32 v8, v182, v208
	v_fmac_f32_e32 v9, v182, v212
	v_fmac_f32_e32 v10, v182, v216
	v_fmac_f32_e32 v11, v182, v220
	v_fmac_f32_e32 v12, v182, v224
	v_fmac_f32_e32 v13, v182, v228
	v_fmac_f32_e32 v16, v182, v232
	v_fmac_f32_e32 v6, v183, v197
	v_fmac_f32_e32 v7, v183, v201
	v_fmac_f32_e32 v8, v183, v209
	v_fmac_f32_e32 v9, v183, v213
	v_fmac_f32_e32 v10, v183, v217
	v_fmac_f32_e32 v11, v183, v221
	v_fmac_f32_e32 v12, v183, v225
	v_fmac_f32_e32 v13, v183, v229
	v_fmac_f32_e32 v16, v183, v233
	v_fmac_f32_e32 v6, v184, v198
	v_fmac_f32_e32 v7, v184, v202
	v_fmac_f32_e32 v8, v184, v210
	v_fmac_f32_e32 v9, v184, v214
	v_fmac_f32_e32 v10, v184, v218
	v_fmac_f32_e32 v11, v184, v222
	v_fmac_f32_e32 v12, v184, v226
	v_fmac_f32_e32 v13, v184, v230
	v_fmac_f32_e32 v16, v184, v234
	v_fmac_f32_e32 v6, v185, v199
	v_fmac_f32_e32 v7, v185, v203
	v_fmac_f32_e32 v8, v185, v211
	v_fmac_f32_e32 v9, v185, v215
	v_fmac_f32_e32 v10, v185, v219
	v_fmac_f32_e32 v11, v185, v223
	v_fmac_f32_e32 v12, v185, v227
	v_fmac_f32_e32 v13, v185, v231
	v_fmac_f32_e32 v16, v185, v235
	ds_read_b128 v[196:199], v17 offset:224
	ds_read_b128 v[200:203], v17 offset:4320
	ds_read_b128 v[208:211], v17 offset:8416
	ds_read_b128 v[212:215], v17 offset:12512
	ds_read_b128 v[216:219], v17 offset:16608
	ds_read_b128 v[220:223], v17 offset:20704
	ds_read_b128 v[224:227], v17 offset:24800
	ds_read_b128 v[228:231], v17 offset:28896
	ds_read_b128 v[232:235], v17 offset:32992
	s_waitcnt lgkmcnt(0)
	v_fmac_f32_e32 v6, v186, v196
	v_fmac_f32_e32 v7, v186, v200
	v_fmac_f32_e32 v8, v186, v208
	v_fmac_f32_e32 v9, v186, v212
	v_fmac_f32_e32 v10, v186, v216
	v_fmac_f32_e32 v11, v186, v220
	v_fmac_f32_e32 v12, v186, v224
	v_fmac_f32_e32 v13, v186, v228
	v_fmac_f32_e32 v16, v186, v232
	v_fmac_f32_e32 v6, v187, v197
	v_fmac_f32_e32 v7, v187, v201
	v_fmac_f32_e32 v8, v187, v209
	v_fmac_f32_e32 v9, v187, v213
	v_fmac_f32_e32 v10, v187, v217
	v_fmac_f32_e32 v11, v187, v221
	v_fmac_f32_e32 v12, v187, v225
	v_fmac_f32_e32 v13, v187, v229
	v_fmac_f32_e32 v16, v187, v233
	v_fmac_f32_e32 v6, v188, v198
	v_fmac_f32_e32 v7, v188, v202
	v_fmac_f32_e32 v8, v188, v210
	v_fmac_f32_e32 v9, v188, v214
	v_fmac_f32_e32 v10, v188, v218
	v_fmac_f32_e32 v11, v188, v222
	v_fmac_f32_e32 v12, v188, v226
	v_fmac_f32_e32 v13, v188, v230
	v_fmac_f32_e32 v16, v188, v234
	v_fmac_f32_e32 v6, v189, v199
	v_fmac_f32_e32 v7, v189, v203
	v_fmac_f32_e32 v8, v189, v211
	v_fmac_f32_e32 v9, v189, v215
	v_fmac_f32_e32 v10, v189, v219
	v_fmac_f32_e32 v11, v189, v223
	v_fmac_f32_e32 v12, v189, v227
	v_fmac_f32_e32 v13, v189, v231
	v_fmac_f32_e32 v16, v189, v235
	ds_read_b128 v[196:199], v17 offset:240
	ds_read_b128 v[200:203], v17 offset:4336
	ds_read_b128 v[208:211], v17 offset:8432
	ds_read_b128 v[212:215], v17 offset:12528
	ds_read_b128 v[216:219], v17 offset:16624
	ds_read_b128 v[220:223], v17 offset:20720
	ds_read_b128 v[224:227], v17 offset:24816
	ds_read_b128 v[228:231], v17 offset:28912
	ds_read_b128 v[232:235], v17 offset:33008
	s_waitcnt lgkmcnt(0)
	v_fmac_f32_e32 v6, v190, v196
	v_fmac_f32_e32 v7, v190, v200
	v_fmac_f32_e32 v8, v190, v208
	v_fmac_f32_e32 v9, v190, v212
	v_fmac_f32_e32 v10, v190, v216
	v_fmac_f32_e32 v11, v190, v220
	v_fmac_f32_e32 v12, v190, v224
	v_fmac_f32_e32 v13, v190, v228
	v_fmac_f32_e32 v16, v190, v232
	v_fmac_f32_e32 v6, v191, v197
	v_fmac_f32_e32 v7, v191, v201
	v_fmac_f32_e32 v8, v191, v209
	v_fmac_f32_e32 v9, v191, v213
	v_fmac_f32_e32 v10, v191, v217
	v_fmac_f32_e32 v11, v191, v221
	v_fmac_f32_e32 v12, v191, v225
	v_fmac_f32_e32 v13, v191, v229
	v_fmac_f32_e32 v16, v191, v233
	v_fmac_f32_e32 v6, v194, v198
	v_fmac_f32_e32 v7, v194, v202
	v_fmac_f32_e32 v8, v194, v210
	v_fmac_f32_e32 v9, v194, v214
	v_fmac_f32_e32 v10, v194, v218
	v_fmac_f32_e32 v11, v194, v222
	v_fmac_f32_e32 v12, v194, v226
	v_fmac_f32_e32 v13, v194, v230
	v_fmac_f32_e32 v16, v194, v234
	v_fmac_f32_e32 v6, v195, v199
	v_fmac_f32_e32 v7, v195, v203
	v_fmac_f32_e32 v8, v195, v211
	v_fmac_f32_e32 v9, v195, v215
	v_fmac_f32_e32 v10, v195, v219
	v_fmac_f32_e32 v11, v195, v223
	v_fmac_f32_e32 v12, v195, v227
	v_fmac_f32_e32 v13, v195, v231
	v_fmac_f32_e32 v16, v195, v235
	v_mad_u32_u24 v4, v2, 36, v82
	v_add_u32_e32 v5, 0x9000, v4
	ds_write2_b32 v5, v6, v7 offset1:1
	v_add_u32_e32 v5, 0x9008, v4
	ds_write2_b32 v5, v8, v9 offset1:1
	v_add_u32_e32 v5, 0x9010, v4
	s_movk_i32 s8, 0x90
	ds_write2_b32 v5, v10, v11 offset1:1
	v_add_u32_e32 v5, 0x9018, v4
	v_cmp_gt_u32_e32 vcc, s8, v2
	ds_write2_b32 v5, v12, v13 offset1:1
	ds_write_b32 v4, v16 offset:36896
	s_waitcnt lgkmcnt(0)
	s_barrier
	s_and_saveexec_b64 s[8:9], vcc
	s_cbranch_execz .LBB0_7
	s_load_dwordx16 s[36:51], s[0:1], 0x0
	v_lshl_or_b32 v4, v14, 4, v15
	v_ashrrev_i32_e32 v5, 31, v4
	v_mul_u32_u24_e32 v2, 36, v15
	s_movk_i32 s10, 0xc00
	s_waitcnt lgkmcnt(0)
	v_lshl_add_u64 v[6:7], v[4:5], 2, s[48:49]
	global_load_dword v20, v[6:7], off
	v_lshlrev_b32_e32 v5, 2, v3
	v_add3_u32 v5, v82, v2, v5
	v_mad_u32_u24 v2, v3, s10, v4
	v_add_u32_e32 v4, 0x9000, v5
	v_add_u32_e32 v6, 0x9400, v5
	v_add_u32_e32 v8, 0x9800, v5
	v_add_u32_e32 v10, 0x9c00, v5
	v_add_u32_e32 v12, 0xa200, v5
	v_add_u32_e32 v14, 0xa600, v5
	v_add_u32_e32 v16, 0xaa00, v5
	v_add_u32_e32 v18, 0xae00, v5
	ds_read2_b32 v[4:5], v4 offset1:144
	ds_read2_b32 v[6:7], v6 offset0:32 offset1:176
	ds_read2_b32 v[8:9], v8 offset0:64 offset1:208
	ds_read2_b32 v[10:11], v10 offset0:96 offset1:240
	ds_read2_b32 v[12:13], v12 offset1:144
	ds_read2_b32 v[14:15], v14 offset0:32 offset1:176
	ds_read2_b32 v[16:17], v16 offset0:64 offset1:208
	ds_read2_b32 v[18:19], v18 offset0:96 offset1:240
	s_load_dwordx16 s[12:27], s[0:1], 0xc0
	v_ashrrev_i32_e32 v3, 31, v2
	s_waitcnt lgkmcnt(0)
	v_lshl_add_u64 v[2:3], v[2:3], 2, s[14:15]
	s_waitcnt vmcnt(0)
	v_add_f32_e32 v4, v20, v4
	v_add_f32_e32 v4, v4, v5
	v_add_f32_e32 v4, v4, v6
	v_add_f32_e32 v4, v4, v7
	v_add_f32_e32 v4, v4, v8
	v_add_f32_e32 v4, v4, v9
	v_add_f32_e32 v4, v4, v10
	v_add_f32_e32 v4, v4, v11
	v_add_f32_e32 v4, v4, v12
	v_add_f32_e32 v4, v4, v13
	v_add_f32_e32 v4, v4, v14
	v_add_f32_e32 v4, v4, v15
	v_add_f32_e32 v4, v4, v16
	v_add_f32_e32 v4, v4, v17
	v_add_f32_e32 v4, v4, v18
	v_add_f32_e32 v4, v4, v19
	global_store_dword v[2:3], v4, off
	s_branch .LBB0_7
